# v22: same as v20 with table-build stride derived from gridDim (robustness)
# speedup vs baseline: 1.0456x; 1.0005x over previous
.LBB0_583:
	s_or_b64 exec, exec, s[60:61]
	s_waitcnt vmcnt(0)
	s_cmp_lt_u32 s2, 0x100
	s_cbranch_scc1 .Lmy_tq_skip
	v_ashrrev_i32_e32 v70, 6, v104
	v_subrev_u32_e32 v70, 0x400, v70
	s_sub_u32 s24, s33, 0x100
	s_lshl_b32 s24, s24, 2
	v_mbcnt_lo_u32_b32 v255, -1, 0
	v_mov_b32_e32 v242, v98
	v_mov_b32_e32 v244, v102
	s_mov_b64 s[22:23], exec
	v_mbcnt_hi_u32_b32 v0, -1, v255
	v_and_b32_e32 v1, 64, v0
	v_add_u32_e32 v1, 64, v1
	v_xor_b32_e32 v2, 16, v0
	v_cmp_lt_i32_e32 vcc, v2, v1
	v_readlane_b32 s36, v238, 0
	v_readlane_b32 s37, v238, 1
	v_cndmask_b32_e32 v2, v0, v2, vcc
	v_lshlrev_b32_e32 v71, 2, v2
	v_xor_b32_e32 v2, 8, v0
	v_cmp_lt_i32_e32 vcc, v2, v1
	v_readlane_b32 s38, v238, 2
	v_readlane_b32 s39, v238, 3
	v_cndmask_b32_e32 v2, v0, v2, vcc
	v_lshlrev_b32_e32 v72, 2, v2
	v_xor_b32_e32 v2, 4, v0
	v_cmp_lt_i32_e32 vcc, v2, v1
	v_readlane_b32 s40, v238, 4
	v_readlane_b32 s41, v238, 5
	v_cndmask_b32_e32 v2, v0, v2, vcc
	v_lshlrev_b32_e32 v73, 2, v2
	v_xor_b32_e32 v2, 2, v0
	v_cmp_lt_i32_e32 vcc, v2, v1
	v_readlane_b32 s42, v238, 6
	v_readlane_b32 s43, v238, 7
	v_cndmask_b32_e32 v2, v0, v2, vcc
	v_lshlrev_b32_e32 v74, 2, v2
	v_xor_b32_e32 v2, 1, v0
	v_readlane_b32 s44, v238, 8
	v_readlane_b32 s45, v238, 9
	v_readlane_b32 s46, v238, 10
	v_readlane_b32 s47, v238, 11
	v_readlane_b32 s48, v238, 12
	v_readlane_b32 s49, v238, 13
	v_readlane_b32 s50, v238, 14
	v_readlane_b32 s51, v238, 15
	v_cmp_lt_i32_e32 vcc, v2, v1
	v_mov_b32_e32 v77, s49
	v_mov_b32_e32 v78, s51
	v_mov_b32_e32 v79, s48
	v_mov_b32_e32 v80, s50
	v_readlane_b32 s36, v238, 16
	v_mov_b32_e32 v247, 0
	v_cndmask_b32_e32 v0, v0, v2, vcc
	v_readlane_b32 s40, v238, 20
	v_readlane_b32 s41, v238, 21
	v_readlane_b32 s42, v238, 22
	v_readlane_b32 s43, v238, 23
	v_mov_b32_e32 v243, v247
	v_cmp_eq_u32_e64 s[0:1], 0, v101
	v_lshlrev_b32_e32 v75, 2, v0
	v_lshl_or_b32 v76, v70, 1, v107
	s_lshl_b32 s12, s24, 1
	s_mov_b64 s[10:11], 0
	s_movk_i32 s13, 0x3fff
	v_lshlrev_b32_e32 v34, 2, v244
	v_mov_b32_e32 v35, v247
	v_mov_b32_e32 v81, s41
	v_mov_b32_e32 v82, s43
	v_mov_b32_e32 v83, s40
	v_mov_b32_e32 v84, s42
	s_mov_b32 s94, 0x40c00000
	s_mov_b32 s95, 0x3e800000
	s_mov_b32 s96, 0x3f400000
	s_mov_b32 s97, 0x3fa00000
	s_mov_b32 s14, 0x3fe00000
	s_mov_b32 s15, 0x40600000
	s_mov_b32 s3, 0x40200000
	s_mov_b32 s20, 0x40a00000
	v_readlane_b32 s37, v238, 17
	v_readlane_b32 s38, v238, 18
	v_readlane_b32 s39, v238, 19
	v_readlane_b32 s44, v238, 24
	v_readlane_b32 s45, v238, 25
	v_readlane_b32 s46, v238, 26
	v_readlane_b32 s47, v238, 27
	v_readlane_b32 s48, v238, 28
	v_readlane_b32 s49, v238, 29
	v_readlane_b32 s50, v238, 30
	v_readlane_b32 s51, v238, 31
	s_branch .Lmy_tq_20
